# speedup vs baseline: 1.0322x; 1.0232x over previous
;   __device__ __forceinline__ const float* in(int i) const { return ((const float* const*)(ws + OFF_TBL))[i]; }
; __device__ __forceinline__ int ltid() { int t = threadIdx.x; asm volatile("" : "+v"(t)); return t; }
; __device__ void hp_phase(const Ctx& p, const int hd) {
;   char* ws = p.ws;
;   const u16* hh = (const u16*)(ws + OFF_KH); const u16* Uh = (const u16*)(ws + OFF_UH);
;   u16* cat = (u16*)(ws + OFF_CAT1);
;   const float* wv = p.in(18); const float* ng = p.in(21); const float* sk = p.in(22);
;   const int tid = ltid(), w = tid >> 6, lane = tid & 63;
;   float ngr[32], skr[32];
; #pragma unroll
;   for (int k = 0; k < 4; ++k)
; #pragma unroll
;     for (int e = 0; e < 8; ++e) { ngr[k * 8 + e] = ng[hd * 2048 + k * 512 + lane * 8 + e]; skr[k * 8 + e] = sk[hd * 2048 + k * 512 + lane * 8 + e]; }
;   for (int item = blockIdx.x; item < NTOK / 8; item += gridDim.x) {
.LBB0_415:
	s_and_b64 vcc, exec, s[0:1]
	s_cbranch_vccz .LBB0_605
	s_mul_i32 s0, s8, 0xcd
	s_bfe_u32 s16, s0, 0x6000a
	s_mul_i32 s0, s16, 5
	s_sub_i32 s0, s8, s0
	s_and_b32 s14, s0, 0xff
	s_lshl_b32 s20, s16, 13
	s_lshl_b32 s21, s16, 11
	s_cmp_lt_i32 s14, 2
	s_mov_b64 s[0:1], -1
	s_cbranch_scc1 .LBB0_484
	s_and_b32 s4, 0xffff, s14
	s_cmp_lt_i32 s4, 3
	s_cbranch_scc1 .LBB0_475
	s_cmp_lg_u32 s4, 3
	s_cbranch_scc0 .LBB0_423
	v_mov_b32_e32 v0, s66
	s_waitcnt vmcnt(0) lgkmcnt(0)
	v_add_co_u32_e32 v2, vcc, 0x4375c000, v0
	v_mov_b32_e32 v0, s67
	s_nop 0
	v_addc_co_u32_e32 v3, vcc, 0, v0, vcc
	global_load_dwordx2 v[66:67], v[2:3], off offset:144
	global_load_dwordx4 v[58:61], v[2:3], off offset:168
	v_readlane_b32 s0, v253, 20
	v_readlane_b32 s1, v253, 21
	v_mov_b32_e32 v68, v139
	s_andn2_b64 vcc, exec, s[0:1]
	s_movk_i32 s6, 0x4400
	s_movk_i32 s7, 0x1080
	s_cbranch_vccnz .LBB0_422
	v_lshlrev_b32_e32 v0, 3, v68
	v_and_b32_e32 v69, 0x1f8, v0
	v_or_b32_e32 v70, s21, v69
	v_lshlrev_b32_e32 v0, 2, v70
	s_waitcnt vmcnt(0) lgkmcnt(0)
	v_lshl_add_u64 v[22:23], v[58:59], 0, v[0:1]
	v_lshl_add_u64 v[30:31], v[60:61], 0, v[0:1]
	global_load_dwordx4 v[2:5], v[22:23], off
	global_load_dwordx4 v[6:9], v[22:23], off offset:16
	global_load_dwordx4 v[10:13], v[30:31], off
	global_load_dwordx4 v[14:17], v[30:31], off offset:16
	global_load_dwordx4 v[18:21], v[22:23], off offset:2048
	s_nop 0
	global_load_dwordx4 v[22:25], v[22:23], off offset:2064
	s_nop 0
	global_load_dwordx4 v[26:29], v[30:31], off offset:2048
	s_nop 0
	global_load_dwordx4 v[30:33], v[30:31], off offset:2064
	v_or_b32_e32 v71, 0x400, v70
	v_or_b32_e32 v72, 0x600, v70
	v_lshlrev_b32_e32 v34, 2, v71
	v_mov_b32_e32 v35, v1
	v_or_b32_e32 v42, 0x1010, v0
	v_mov_b32_e32 v43, v1
	v_lshlrev_b32_e32 v50, 2, v72
	v_mov_b32_e32 v51, v1
	v_or_b32_e32 v0, 0x1810, v0
	v_lshl_add_u64 v[36:37], v[58:59], 0, v[34:35]
	v_lshl_add_u64 v[38:39], v[60:61], 0, v[34:35]
	v_lshl_add_u64 v[44:45], v[58:59], 0, v[42:43]
	v_lshl_add_u64 v[46:47], v[60:61], 0, v[42:43]
	v_lshl_add_u64 v[52:53], v[58:59], 0, v[50:51]
	v_lshl_add_u64 v[54:55], v[60:61], 0, v[50:51]
	v_lshl_add_u64 v[58:59], v[58:59], 0, v[0:1]
	v_lshl_add_u64 v[62:63], v[60:61], 0, v[0:1]
	global_load_dwordx4 v[34:37], v[36:37], off
	s_nop 0
	global_load_dwordx4 v[38:41], v[38:39], off
	s_nop 0
	global_load_dwordx4 v[42:45], v[44:45], off
	s_nop 0
	global_load_dwordx4 v[46:49], v[46:47], off
	s_nop 0
	global_load_dwordx4 v[50:53], v[52:53], off
	s_nop 0
	global_load_dwordx4 v[54:57], v[54:55], off
	s_nop 0
	global_load_dwordx4 v[58:61], v[58:59], off
	s_nop 0
	global_load_dwordx4 v[62:65], v[62:63], off
	v_ashrrev_i32_e32 v82, 6, v68
	v_add_u32_e32 v0, 64, v196
	v_xor_b32_e32 v68, 32, v195
	v_cmp_lt_i32_e32 vcc, v68, v0
	s_lshl_b32 s0, s21, 1
	s_add_u32 s0, s66, s0
	v_cndmask_b32_e32 v68, v195, v68, vcc
	v_lshlrev_b32_e32 v141, 2, v68
	v_xor_b32_e32 v68, 16, v195
	v_cmp_lt_i32_e32 vcc, v68, v0
	s_mov_b64 s[4:5], 0x4200000
	s_addc_u32 s1, s67, 0
	v_cndmask_b32_e32 v68, v195, v68, vcc
	v_lshlrev_b32_e32 v211, 2, v68
	v_xor_b32_e32 v68, 8, v195
	v_cmp_lt_i32_e32 vcc, v68, v0
	v_ashrrev_i32_e32 v83, 31, v82
	s_nop 0
	v_cndmask_b32_e32 v68, v195, v68, vcc
	v_lshlrev_b32_e32 v212, 2, v68
	v_xor_b32_e32 v68, 4, v195
	v_cmp_lt_i32_e32 vcc, v68, v0
	s_nop 1
	v_cndmask_b32_e32 v68, v195, v68, vcc
	v_lshlrev_b32_e32 v213, 2, v68
	v_xor_b32_e32 v68, 2, v195
	v_cmp_lt_i32_e32 vcc, v68, v0
	s_nop 1
	v_cndmask_b32_e32 v68, v195, v68, vcc
	v_lshlrev_b32_e32 v214, 2, v68
	v_xor_b32_e32 v68, 1, v195
	v_cmp_lt_i32_e32 vcc, v68, v0
	s_nop 1
	v_cndmask_b32_e32 v0, v195, v68, vcc
	v_lshlrev_b32_e32 v215, 2, v0
	v_lshlrev_b32_e32 v0, 4, v70
	v_lshl_add_u64 v[84:85], v[66:67], 0, v[0:1]
	v_or_b32_e32 v0, 0x2000, v0
	v_lshl_add_u64 v[86:87], v[66:67], 0, v[0:1]
	v_lshlrev_b32_e32 v0, 4, v71
	v_lshl_add_u64 v[88:89], v[66:67], 0, v[0:1]
	v_lshlrev_b32_e32 v0, 4, v72
	v_lshl_add_u64 v[90:91], v[66:67], 0, v[0:1]
	v_and_b32_e32 v230, 63, v139
	v_lshlrev_b32_e32 v230, 7, v230
	v_lshlrev_b32_e32 v228, 4, v70
	v_sub_u32_e32 v228, v228, v230
	v_lshl_add_u32 v228, v139, 6, v228
	v_mov_b32_e32 v229, 0
	v_lshl_add_u64 v[242:243], v[66:67], 0, v[228:229]
	global_load_dwordx4 v[244:247], v[242:243], off
	global_load_dwordx4 v[248:251], v[242:243], off offset:16
	v_lshlrev_b32_e32 v241, 6, v139
	v_add_u32_e32 v241, 0x400, v241
	v_add_u32_e32 v240, 0x400, v230
	s_waitcnt vmcnt(0)
	ds_write_b128 v241, v[244:247]
	ds_write_b128 v241, v[248:251] offset:16
	s_nop 2
	global_load_dwordx4 v[244:247], v[242:243], off offset:32
	global_load_dwordx4 v[248:251], v[242:243], off offset:48
	s_waitcnt vmcnt(0)
	ds_write_b128 v241, v[244:247] offset:32
	ds_write_b128 v241, v[248:251] offset:48
	s_waitcnt lgkmcnt(0)
	s_barrier
	v_lshlrev_b32_e32 v0, 1, v69
	v_lshl_add_u64 v[66:67], s[66:67], 0, v[0:1]
	v_lshl_add_u64 v[92:93], v[66:67], 0, s[4:5]
	s_mov_b64 s[4:5], 0x3b000000
	v_lshl_add_u64 v[94:95], v[66:67], 0, s[4:5]
	v_lshl_add_u64 v[66:67], s[0:1], 0, v[0:1]
	s_mov_b64 s[0:1], 0x20800000
	v_lshl_add_u64 v[96:97], v[66:67], 0, s[0:1]
	s_mov_b32 s0, s63
; __device__ __forceinline__ float bf2f(u16 h) { return __uint_as_float(((unsigned)h) << 16); }
; __device__ void hp_phase(const Ctx& p, const int hd) {
;     ...
;   for (int item = blockIdx.x; item < NTOK / 8; item += gridDim.x) {
;     const long row = (long)item * 8 + w;
;     float hv[32];
;     float s = 0.f;
; #pragma unroll
;     for (int k = 0; k < 4; ++k) {
;       const int c = k * 512 + lane * 8;
;       uint4 r = *(const uint4*)(hh + row * LDQ + c);
;       float x[8] = {bf2f(r.x & 0xffff), bf2f(r.x >> 16), bf2f(r.y & 0xffff), bf2f(r.y >> 16),
;                     bf2f(r.z & 0xffff), bf2f(r.z >> 16), bf2f(r.w & 0xffff), bf2f(r.w >> 16)};
; #pragma unroll
;       for (int nb = 0; nb < 2; ++nb) {
;         const float* W = wv + ((hd * 2048 + c) / 4 + nb) * 16;
; #pragma unroll
;         for (int o = 0; o < 4; ++o) {
;           float a = 0.f;
; #pragma unroll
;           for (int i = 0; i < 4; ++i) a += x[nb * 4 + i] * W[i * 4 + o];
;           hv[k * 8 + nb * 4 + o] = a; s += a;
;         }
;       }
;     }
;     ...
;     for (int k = 0; k < 4; ++k) {
;       const int c = k * 512 + lane * 8;
;       uint4 ur = *(const uint4*)(Uh + row * LDQ + c);
;       uint4 zr = *(const uint4*)(cat + row * 8704 + hd * 2048 + c);
.LBB0_421:
	s_ashr_i32 s1, s0, 31
	v_lshl_add_u64 v[146:147], s[0:1], 3, v[82:83]
	v_mad_u64_u32 v[98:99], s[4:5], v146, s7, v[92:93]
	v_mad_i32_i24 v99, v147, s7, v99
	global_load_dwordx4 v[66:69], v[98:99], off
	global_load_dwordx4 v[244:247], v[98:99], off offset:1024
	global_load_dwordx4 v[248:251], v[98:99], off offset:2048
	global_load_dwordx4 v[228:231], v[98:99], off offset:3072
	ds_read_b128 v[106:109], v240 offset:24672
	ds_read_b128 v[158:161], v240 offset:24688
	ds_read_b128 v[172:175], v240 offset:32
	ds_read_b128 v[176:179], v240 offset:48
	s_add_i32 s0, s0, s96
	s_cmpk_gt_i32 s0, 0x7ff
	ds_read_b128 v[102:105], v240 offset:24656
	ds_read_b128 v[168:171], v240 offset:16
	s_waitcnt vmcnt(0) lgkmcnt(0)
	v_lshlrev_b32_e32 v112, 16, v66
	v_and_b32_e32 v116, 0xffff0000, v66
	v_lshlrev_b32_e32 v148, 16, v67
	v_and_b32_e32 v150, 0xffff0000, v67
	v_lshlrev_b32_e32 v118, 16, v68
	v_and_b32_e32 v120, 0xffff0000, v68
	v_lshlrev_b32_e32 v152, 16, v69
	v_and_b32_e32 v156, 0xffff0000, v69
	v_lshlrev_b32_e32 v122, 16, v244
	v_and_b32_e32 v132, 0xffff0000, v244
	v_lshlrev_b32_e32 v144, 16, v245
	v_and_b32_e32 v154, 0xffff0000, v245
	v_lshlrev_b32_e32 v124, 16, v246
	v_and_b32_e32 v134, 0xffff0000, v246
	v_lshlrev_b32_e32 v136, 16, v247
	v_and_b32_e32 v142, 0xffff0000, v247
	v_lshlrev_b32_e32 v78, 16, v249
	v_and_b32_e32 v80, 0xffff0000, v249
	v_lshlrev_b32_e32 v74, 16, v248
	v_and_b32_e32 v76, 0xffff0000, v248
	v_lshlrev_b32_e32 v66, 16, v250
	v_and_b32_e32 v68, 0xffff0000, v250
	v_lshlrev_b32_e32 v70, 16, v251
	v_and_b32_e32 v72, 0xffff0000, v251
	v_lshlrev_b32_e32 v0, 16, v228
	v_and_b32_e32 v126, 0xffff0000, v228
	v_lshlrev_b32_e32 v128, 16, v229
	v_and_b32_e32 v130, 0xffff0000, v229
	v_lshlrev_b32_e32 v110, 16, v230
	v_and_b32_e32 v162, 0xffff0000, v230
	v_lshlrev_b32_e32 v164, 16, v231
	v_and_b32_e32 v166, 0xffff0000, v231
	ds_read_b128 v[98:101], v240 offset:24640
	s_waitcnt vmcnt(0) lgkmcnt(0)
	v_pk_fma_f32 v[98:99], v[98:99], v[110:111], 0 op_sel_hi:[1,0,0]
	s_nop 0
	v_pk_fma_f32 v[98:99], v[102:103], v[162:163], v[98:99] op_sel_hi:[1,0,1]
	s_nop 0
	v_pk_fma_f32 v[98:99], v[106:107], v[164:165], v[98:99] op_sel_hi:[1,0,1]
	s_nop 0
	v_pk_fma_f32 v[114:115], v[158:159], v[166:167], v[98:99] op_sel_hi:[1,0,1]
	v_pk_fma_f32 v[98:99], v[100:101], v[110:111], 0 op_sel_hi:[1,0,0]
	v_mad_u64_u32 v[100:101], s[4:5], v146, s7, v[94:95]
	v_pk_fma_f32 v[98:99], v[104:105], v[162:163], v[98:99] op_sel_hi:[1,0,1]
	v_mad_i32_i24 v101, v147, s7, v101
	v_pk_fma_f32 v[98:99], v[108:109], v[164:165], v[98:99] op_sel_hi:[1,0,1]
	global_load_dwordx4 v[104:107], v[100:101], off
	v_pk_fma_f32 v[110:111], v[160:161], v[166:167], v[98:99] op_sel_hi:[1,0,1]
	ds_read_b128 v[164:167], v240
	v_mad_u64_u32 v[98:99], s[4:5], v146, s6, v[96:97]
	v_mad_i32_i24 v99, v147, s6, v99
	global_load_dwordx4 v[160:163], v[98:99], off
	global_load_dwordx4 v[244:247], v[98:99], off offset:1024
	global_load_dwordx4 v[248:251], v[98:99], off offset:2048
	global_load_dwordx4 v[228:231], v[98:99], off offset:3072
	s_waitcnt vmcnt(0) lgkmcnt(0)
	v_and_b32_e32 v103, 0xffff0000, v107
	v_lshlrev_b32_e32 v102, 16, v107
	v_pk_fma_f32 v[146:147], v[164:165], v[112:113], 0 op_sel_hi:[1,0,0]
	v_pk_fma_f32 v[112:113], v[166:167], v[112:113], 0 op_sel_hi:[1,0,0]
	ds_read_b128 v[164:167], v240 offset:64
	v_pk_fma_f32 v[146:147], v[168:169], v[116:117], v[146:147] op_sel_hi:[1,0,1]
	v_pk_fma_f32 v[112:113], v[170:171], v[116:117], v[112:113] op_sel_hi:[1,0,1]
	ds_read_b128 v[168:171], v240 offset:80
	v_pk_fma_f32 v[146:147], v[172:173], v[148:149], v[146:147] op_sel_hi:[1,0,1]
	v_pk_fma_f32 v[112:113], v[174:175], v[148:149], v[112:113] op_sel_hi:[1,0,1]
	ds_read_b128 v[172:175], v240 offset:96
	v_pk_fma_f32 v[146:147], v[176:177], v[150:151], v[146:147] op_sel_hi:[1,0,1]
	v_pk_fma_f32 v[148:149], v[178:179], v[150:151], v[112:113] op_sel_hi:[1,0,1]
	ds_read_b128 v[176:179], v240 offset:112
	v_and_b32_e32 v181, 0xffff0000, v161
	v_mul_f32_e32 v67, 0xbfb8aa3b, v181
	v_exp_f32_e32 v67, v67
	v_lshlrev_b32_e32 v180, 16, v161
	v_and_b32_e32 v159, 0xffff0000, v163
	v_lshlrev_b32_e32 v158, 16, v163
	v_add_f32_e32 v67, 1.0, v67
	v_rcp_f32_e32 v113, v67
	v_mul_f32_e32 v67, 0xbfb8aa3b, v180
	v_exp_f32_e32 v67, v67
	v_and_b32_e32 v163, 0xffff0000, v162
	v_lshlrev_b32_e32 v162, 16, v162
	v_and_b32_e32 v161, 0xffff0000, v160
	v_add_f32_e32 v67, 1.0, v67
	v_rcp_f32_e32 v112, v67
	v_mul_f32_e32 v67, 0xbfb8aa3b, v163
	v_exp_f32_e32 v67, v67
	v_lshlrev_b32_e32 v160, 16, v160
	v_pk_mul_f32 v[112:113], v[112:113], v[180:181]
	v_and_b32_e32 v107, 0xffff0000, v106
	v_add_f32_e32 v67, 1.0, v67
	v_lshlrev_b32_e32 v106, 16, v106
	v_and_b32_e32 v109, 0xffff0000, v105
	v_lshlrev_b32_e32 v108, 16, v105
	v_and_b32_e32 v105, 0xffff0000, v104
	v_lshlrev_b32_e32 v104, 16, v104
	ds_read_b128 v[180:183], v240 offset:8304
	s_waitcnt vmcnt(0) lgkmcnt(0)
	v_pk_fma_f32 v[116:117], v[164:165], v[118:119], 0 op_sel_hi:[1,0,0]
	v_pk_fma_f32 v[118:119], v[166:167], v[118:119], 0 op_sel_hi:[1,0,0]
	v_pk_fma_f32 v[116:117], v[168:169], v[120:121], v[116:117] op_sel_hi:[1,0,1]
	v_pk_fma_f32 v[118:119], v[170:171], v[120:121], v[118:119] op_sel_hi:[1,0,1]
	ds_read_b128 v[168:171], v240 offset:8208
	v_pk_fma_f32 v[116:117], v[172:173], v[152:153], v[116:117] op_sel_hi:[1,0,1]
	v_pk_fma_f32 v[118:119], v[174:175], v[152:153], v[118:119] op_sel_hi:[1,0,1]
	ds_read_b128 v[172:175], v240 offset:8224
	v_pk_fma_f32 v[150:151], v[176:177], v[156:157], v[116:117] op_sel_hi:[1,0,1]
	v_rcp_f32_e32 v117, v67
	v_mul_f32_e32 v67, 0xbfb8aa3b, v162
	v_exp_f32_e32 v67, v67
	v_pk_fma_f32 v[152:153], v[178:179], v[156:157], v[118:119] op_sel_hi:[1,0,1]
	ds_read_b128 v[176:179], v240 offset:8240
	v_add_f32_e32 v67, 1.0, v67
	v_rcp_f32_e32 v116, v67
	v_mul_f32_e32 v67, 0xbfb8aa3b, v159
	v_exp_f32_e32 v67, v67
	v_pk_mul_f32 v[116:117], v[116:117], v[162:163]
	v_add_f32_e32 v67, 1.0, v67
	v_rcp_f32_e32 v119, v67
	v_mul_f32_e32 v67, 0xbfb8aa3b, v158
	v_exp_f32_e32 v67, v67
	s_nop 0
	v_add_f32_e32 v67, 1.0, v67
	v_rcp_f32_e32 v118, v67
	v_mul_f32_e32 v67, 0xbfb8aa3b, v161
	v_exp_f32_e32 v67, v67
	v_pk_mul_f32 v[120:121], v[118:119], v[158:159]
	v_add_f32_e32 v67, 1.0, v67
	v_rcp_f32_e32 v119, v67
	v_mul_f32_e32 v67, 0xbfb8aa3b, v160
	v_exp_f32_e32 v67, v67
	s_nop 0
	v_add_f32_e32 v67, 1.0, v67
	v_rcp_f32_e32 v118, v67
	s_nop 0
	v_pk_mul_f32 v[118:119], v[118:119], v[160:161]
	s_waitcnt vmcnt(0) lgkmcnt(0)
; __device__ __forceinline__ float bf2f(u16 h) { return __uint_as_float(((unsigned)h) << 16); }
; __device__ __forceinline__ float siluf(float x) { return x * __builtin_amdgcn_rcpf(1.f + __expf(-x)); }
; __device__ void hp_phase(const Ctx& p, const int hd) {
;     ...
;       for (int nb = 0; nb < 2; ++nb) {
;         const float* W = wv + ((hd * 2048 + c) / 4 + nb) * 16;
; #pragma unroll
;         for (int o = 0; o < 4; ++o) {
;           float a = 0.f;
; #pragma unroll
;           for (int i = 0; i < 4; ++i) a += x[nb * 4 + i] * W[i * 4 + o];
;           hv[k * 8 + nb * 4 + o] = a; s += a;
;         }
;       }
;     }
;     ...
;       float u[8] = {bf2f(ur.x & 0xffff), bf2f(ur.x >> 16), bf2f(ur.y & 0xffff), bf2f(ur.y >> 16),
;                     bf2f(ur.z & 0xffff), bf2f(ur.z >> 16), bf2f(ur.w & 0xffff), bf2f(ur.w >> 16)};
;       float z[8] = {bf2f(zr.x & 0xffff), bf2f(zr.x >> 16), bf2f(zr.y & 0xffff), bf2f(zr.y >> 16),
;                     bf2f(zr.z & 0xffff), bf2f(zr.z >> 16), bf2f(zr.w & 0xffff), bf2f(zr.w >> 16)};
;       float o[8];
; #pragma unroll
;       for (int e = 0; e < 8; ++e) {
;         o[e] = (hv[k * 8 + e] * rs * ngr[k * 8 + e] + skr[k * 8 + e] * u[e]) * siluf(z[e]);
	v_and_b32_e32 v159, 0xffff0000, v247
	v_lshlrev_b32_e32 v158, 16, v247
	v_and_b32_e32 v167, 0xffff0000, v246
	v_lshlrev_b32_e32 v166, 16, v246
	v_and_b32_e32 v165, 0xffff0000, v245
	v_lshlrev_b32_e32 v164, 16, v245
	v_and_b32_e32 v157, 0xffff0000, v244
	v_lshlrev_b32_e32 v156, 16, v244
	ds_read_b128 v[160:163], v240 offset:8192
	v_mul_f32_e32 v67, 0xbfb8aa3b, v165
	v_exp_f32_e32 v67, v67
	s_waitcnt vmcnt(0) lgkmcnt(0)
	v_pk_fma_f32 v[160:161], v[160:161], v[122:123], 0 op_sel_hi:[1,0,0]
	v_pk_fma_f32 v[122:123], v[162:163], v[122:123], 0 op_sel_hi:[1,0,0]
	v_pk_fma_f32 v[160:161], v[168:169], v[132:133], v[160:161] op_sel_hi:[1,0,1]
	v_pk_fma_f32 v[122:123], v[170:171], v[132:133], v[122:123] op_sel_hi:[1,0,1]
	ds_read_b128 v[168:171], v240 offset:8256
	v_pk_fma_f32 v[160:161], v[172:173], v[144:145], v[160:161] op_sel_hi:[1,0,1]
	v_pk_fma_f32 v[122:123], v[174:175], v[144:145], v[122:123] op_sel_hi:[1,0,1]
	ds_read_b128 v[172:175], v240 offset:8272
	v_pk_fma_f32 v[160:161], v[176:177], v[154:155], v[160:161] op_sel_hi:[1,0,1]
	v_pk_fma_f32 v[162:163], v[178:179], v[154:155], v[122:123] op_sel_hi:[1,0,1]
	ds_read_b128 v[176:179], v240 offset:8288
	v_add_f32_e32 v67, 1.0, v67
	v_rcp_f32_e32 v123, v67
	v_mul_f32_e32 v67, 0xbfb8aa3b, v164
	v_exp_f32_e32 v67, v67
	s_waitcnt vmcnt(0) lgkmcnt(0)
	v_pk_fma_f32 v[132:133], v[168:169], v[124:125], 0 op_sel_hi:[1,0,0]
	v_pk_fma_f32 v[124:125], v[170:171], v[124:125], 0 op_sel_hi:[1,0,0]
	v_add_f32_e32 v67, 1.0, v67
	v_rcp_f32_e32 v122, v67
	v_mul_f32_e32 v67, 0xbfb8aa3b, v167
	v_exp_f32_e32 v67, v67
	v_pk_fma_f32 v[132:133], v[172:173], v[134:135], v[132:133] op_sel_hi:[1,0,1]
	v_pk_mul_f32 v[122:123], v[122:123], v[164:165]
	v_pk_fma_f32 v[132:133], v[176:177], v[136:137], v[132:133] op_sel_hi:[1,0,1]
	v_add_f32_e32 v67, 1.0, v67
	v_pk_fma_f32 v[164:165], v[180:181], v[142:143], v[132:133] op_sel_hi:[1,0,1]
	v_rcp_f32_e32 v133, v67
	v_mul_f32_e32 v67, 0xbfb8aa3b, v166
	v_exp_f32_e32 v67, v67
	v_pk_fma_f32 v[124:125], v[174:175], v[134:135], v[124:125] op_sel_hi:[1,0,1]
	ds_read_b128 v[172:175], v240 offset:16400
	v_pk_fma_f32 v[124:125], v[178:179], v[136:137], v[124:125] op_sel_hi:[1,0,1]
	v_add_f32_e32 v67, 1.0, v67
	v_rcp_f32_e32 v132, v67
	v_mul_f32_e32 v67, 0xbfb8aa3b, v159
	v_exp_f32_e32 v67, v67
	ds_read_b128 v[176:179], v240 offset:16416
	v_pk_mul_f32 v[132:133], v[132:133], v[166:167]
	v_pk_fma_f32 v[166:167], v[182:183], v[142:143], v[124:125] op_sel_hi:[1,0,1]
	v_add_f32_e32 v67, 1.0, v67
	v_rcp_f32_e32 v125, v67
	v_mul_f32_e32 v67, 0xbfb8aa3b, v158
	v_exp_f32_e32 v67, v67
	ds_read_b128 v[180:183], v240 offset:16432
	v_add_f32_e32 v67, 1.0, v67
	v_rcp_f32_e32 v124, v67
	v_mul_f32_e32 v67, 0xbfb8aa3b, v157
	v_exp_f32_e32 v67, v67
	v_pk_mul_f32 v[142:143], v[124:125], v[158:159]
	v_add_f32_e32 v67, 1.0, v67
	v_rcp_f32_e32 v125, v67
	v_mul_f32_e32 v67, 0xbfb8aa3b, v156
	v_exp_f32_e32 v67, v67
	s_waitcnt vmcnt(0) lgkmcnt(0)
	v_and_b32_e32 v155, 0xffff0000, v250
	v_add_f32_e32 v67, 1.0, v67
	v_rcp_f32_e32 v124, v67
	v_lshlrev_b32_e32 v154, 16, v250
	v_and_b32_e32 v145, 0xffff0000, v249
	v_lshlrev_b32_e32 v144, 16, v249
	v_pk_mul_f32 v[134:135], v[124:125], v[156:157]
	v_and_b32_e32 v157, 0xffff0000, v251
	v_lshlrev_b32_e32 v156, 16, v251
	v_and_b32_e32 v125, 0xffff0000, v248
	v_lshlrev_b32_e32 v124, 16, v248
	ds_read_b128 v[168:171], v240 offset:16384
	v_mul_f32_e32 v67, 0xbfb8aa3b, v145
	v_exp_f32_e32 v67, v67
	s_waitcnt vmcnt(0) lgkmcnt(0)
	v_pk_fma_f32 v[158:159], v[168:169], v[74:75], 0 op_sel_hi:[1,0,0]
	v_pk_fma_f32 v[74:75], v[170:171], v[74:75], 0 op_sel_hi:[1,0,0]
	v_add_f32_e32 v67, 1.0, v67
	v_pk_fma_f32 v[74:75], v[174:175], v[76:77], v[74:75] op_sel_hi:[1,0,1]
	v_pk_fma_f32 v[158:159], v[172:173], v[76:77], v[158:159] op_sel_hi:[1,0,1]
	v_pk_fma_f32 v[74:75], v[178:179], v[78:79], v[74:75] op_sel_hi:[1,0,1]
	v_pk_fma_f32 v[158:159], v[176:177], v[78:79], v[158:159] op_sel_hi:[1,0,1]
	v_pk_fma_f32 v[170:171], v[182:183], v[80:81], v[74:75] op_sel_hi:[1,0,1]
	v_rcp_f32_e32 v75, v67
	v_mul_f32_e32 v67, 0xbfb8aa3b, v144
	v_exp_f32_e32 v67, v67
	v_pk_fma_f32 v[168:169], v[180:181], v[80:81], v[158:159] op_sel_hi:[1,0,1]
	ds_read_b128 v[78:81], v240 offset:16464
	ds_read_b128 v[174:177], v240 offset:16480
	ds_read_b128 v[178:181], v240 offset:16496
	v_add_f32_e32 v67, 1.0, v67
	v_rcp_f32_e32 v74, v67
	s_nop 0
	v_pk_mul_f32 v[144:145], v[74:75], v[144:145]
	ds_read_b128 v[74:77], v240 offset:16448
	s_waitcnt vmcnt(0) lgkmcnt(0)
	v_pk_fma_f32 v[74:75], v[74:75], v[66:67], 0 op_sel_hi:[1,0,0]
	v_mul_f32_e32 v67, 0xbfb8aa3b, v155
	v_exp_f32_e32 v67, v67
	v_pk_fma_f32 v[74:75], v[78:79], v[68:69], v[74:75] op_sel_hi:[1,0,1]
	v_add_f32_e32 v67, 1.0, v67
	v_pk_fma_f32 v[74:75], v[174:175], v[70:71], v[74:75] op_sel_hi:[1,0,1]
	s_nop 0
	v_pk_fma_f32 v[174:175], v[178:179], v[72:73], v[74:75] op_sel_hi:[1,0,1]
	v_rcp_f32_e32 v75, v67
	v_mul_f32_e32 v67, 0xbfb8aa3b, v154
	v_exp_f32_e32 v67, v67
	s_nop 0
	v_add_f32_e32 v67, 1.0, v67
	v_rcp_f32_e32 v74, v67
	v_pk_fma_f32 v[66:67], v[76:77], v[66:67], 0 op_sel_hi:[1,0,0]
	v_pk_mul_f32 v[154:155], v[74:75], v[154:155]
	v_pk_fma_f32 v[66:67], v[80:81], v[68:69], v[66:67] op_sel_hi:[1,0,1]
	ds_read_b128 v[74:77], v240 offset:24608
	ds_read_b128 v[78:81], v240 offset:24624
	v_pk_fma_f32 v[66:67], v[176:177], v[70:71], v[66:67] op_sel_hi:[1,0,1]
	s_nop 0
	v_pk_fma_f32 v[176:177], v[180:181], v[72:73], v[66:67] op_sel_hi:[1,0,1]
	v_mul_f32_e32 v66, 0xbfb8aa3b, v157
	v_exp_f32_e32 v66, v66
	ds_read_b128 v[70:73], v240 offset:24592
	v_add_f32_e32 v66, 1.0, v66
	v_rcp_f32_e32 v67, v66
	v_mul_f32_e32 v66, 0xbfb8aa3b, v156
	v_exp_f32_e32 v66, v66
	s_nop 0
	v_add_f32_e32 v66, 1.0, v66
	v_rcp_f32_e32 v66, v66
	s_nop 0
	v_pk_mul_f32 v[158:159], v[66:67], v[156:157]
	v_mul_f32_e32 v66, 0xbfb8aa3b, v125
	v_exp_f32_e32 v66, v66
	s_nop 0
	v_add_f32_e32 v66, 1.0, v66
	v_rcp_f32_e32 v67, v66
	v_mul_f32_e32 v66, 0xbfb8aa3b, v124
	v_exp_f32_e32 v66, v66
	s_nop 0
	v_add_f32_e32 v66, 1.0, v66
	v_rcp_f32_e32 v66, v66
	s_nop 0
	v_pk_mul_f32 v[156:157], v[66:67], v[124:125]
	s_waitcnt vmcnt(0) lgkmcnt(0)
; __device__ __forceinline__ float siluf(float x) { return x * __builtin_amdgcn_rcpf(1.f + __expf(-x)); }
; __device__ void hp_phase(const Ctx& p, const int hd) {
;     ...
;     s = wave_sum(s);
;     const float mu = s * (1.f / 2048.f);
;     float q = 0.f;
; #pragma unroll
;     for (int e = 0; e < 32; ++e) { hv[e] -= mu; q += hv[e] * hv[e]; }
;     q = wave_sum(q);
;     const float rs = rsqrtf(q * (1.f / 2048.f) + 1e-6f);
;     ...
;         o[e] = (hv[k * 8 + e] * rs * ngr[k * 8 + e] + skr[k * 8 + e] * u[e]) * siluf(z[e]);
	v_and_b32_e32 v173, 0xffff0000, v231
	v_lshlrev_b32_e32 v172, 16, v231
	v_and_b32_e32 v179, 0xffff0000, v230
	v_lshlrev_b32_e32 v178, 16, v230
	v_and_b32_e32 v181, 0xffff0000, v229
	v_lshlrev_b32_e32 v180, 16, v229
	v_and_b32_e32 v125, 0xffff0000, v228
	v_lshlrev_b32_e32 v124, 16, v228
	ds_read_b128 v[66:69], v240 offset:24576
	s_waitcnt vmcnt(0) lgkmcnt(0)
	global_load_dwordx4 v[244:247], v[100:101], off offset:1024
	global_load_dwordx4 v[248:251], v[100:101], off offset:2048
	global_load_dwordx4 v[228:231], v[100:101], off offset:3072
	v_pk_fma_f32 v[66:67], v[66:67], v[0:1], 0 op_sel_hi:[1,0,0]
	s_nop 0
	v_pk_fma_f32 v[66:67], v[70:71], v[126:127], v[66:67] op_sel_hi:[1,0,1]
	s_nop 0
	v_pk_fma_f32 v[66:67], v[74:75], v[128:129], v[66:67] op_sel_hi:[1,0,1]
	s_nop 0
	v_pk_fma_f32 v[70:71], v[78:79], v[130:131], v[66:67] op_sel_hi:[1,0,1]
	v_pk_fma_f32 v[66:67], v[68:69], v[0:1], 0 op_sel_hi:[1,0,0]
	v_mul_f32_e32 v0, 0xbfb8aa3b, v181
	v_exp_f32_e32 v0, v0
	v_pk_fma_f32 v[66:67], v[72:73], v[126:127], v[66:67] op_sel_hi:[1,0,1]
	v_add_f32_e32 v0, 1.0, v0
	v_pk_fma_f32 v[66:67], v[76:77], v[128:129], v[66:67] op_sel_hi:[1,0,1]
	v_mul_f32_e32 v76, 0xbfb8aa3b, v173
	v_pk_fma_f32 v[72:73], v[80:81], v[130:131], v[66:67] op_sel_hi:[1,0,1]
	v_rcp_f32_e32 v67, v0
	v_mul_f32_e32 v0, 0xbfb8aa3b, v180
	v_exp_f32_e32 v0, v0
	v_exp_f32_e32 v76, v76
	v_add_f32_e32 v0, 1.0, v0
	v_rcp_f32_e32 v66, v0
	v_add_f32_e32 v0, v146, v147
	v_add_f32_e32 v0, v0, v148
	v_add_f32_e32 v0, v0, v149
	v_add_f32_e32 v0, v0, v150
	v_add_f32_e32 v0, v0, v151
	v_add_f32_e32 v0, v0, v152
	v_add_f32_e32 v0, v0, v153
	v_add_f32_e32 v0, v0, v160
	v_add_f32_e32 v0, v0, v161
	v_add_f32_e32 v0, v0, v162
	v_add_f32_e32 v0, v0, v163
	v_add_f32_e32 v0, v0, v164
	v_add_f32_e32 v0, v0, v165
	v_add_f32_e32 v0, v0, v166
	v_add_f32_e32 v0, v0, v167
	v_add_f32_e32 v0, v0, v168
	v_add_f32_e32 v0, v0, v169
	v_add_f32_e32 v0, v0, v170
	v_add_f32_e32 v0, v0, v171
	v_add_f32_e32 v0, v0, v174
	v_add_f32_e32 v0, v0, v175
	v_add_f32_e32 v0, v0, v176
	v_add_f32_e32 v0, v0, v177
	v_add_f32_e32 v0, v0, v70
	v_add_f32_e32 v0, v0, v71
	v_add_f32_e32 v0, v0, v72
	v_add_f32_e32 v0, v0, v73
	v_add_f32_e32 v0, v0, v114
	v_add_f32_e32 v0, v0, v115
	v_add_f32_e32 v0, v0, v110
	v_add_f32_e32 v0, v0, v111
	ds_bpermute_b32 v68, v141, v0
	v_pk_mul_f32 v[66:67], v[66:67], v[180:181]
	v_add_f32_e32 v76, 1.0, v76
	v_rcp_f32_e32 v77, v76
	v_mul_f32_e32 v76, 0xbfb8aa3b, v172
	s_waitcnt lgkmcnt(0)
	v_add_f32_e32 v0, v0, v68
	ds_bpermute_b32 v68, v211, v0
	v_exp_f32_e32 v76, v76
	s_waitcnt lgkmcnt(0)
	v_add_f32_e32 v0, v0, v68
	ds_bpermute_b32 v68, v212, v0
	v_add_f32_e32 v76, 1.0, v76
	v_rcp_f32_e32 v76, v76
	s_waitcnt lgkmcnt(0)
	v_add_f32_e32 v0, v0, v68
	ds_bpermute_b32 v68, v213, v0
	v_pk_mul_f32 v[76:77], v[76:77], v[172:173]
	s_waitcnt lgkmcnt(0)
	v_add_f32_e32 v0, v0, v68
	ds_bpermute_b32 v68, v214, v0
	s_waitcnt lgkmcnt(0)
	v_add_f32_e32 v0, v0, v68
	ds_bpermute_b32 v68, v215, v0
	s_waitcnt lgkmcnt(0)
	v_add_f32_e32 v0, v0, v68
	v_mul_f32_e32 v0, 0x3a000000, v0
	v_pk_add_f32 v[180:181], v[146:147], v[0:1] op_sel_hi:[1,0] neg_lo:[0,1] neg_hi:[0,1]
	v_pk_add_f32 v[182:183], v[148:149], v[0:1] op_sel_hi:[1,0] neg_lo:[0,1] neg_hi:[0,1]
	v_pk_mul_f32 v[216:217], v[180:181], v[180:181]
	v_pk_mul_f32 v[218:219], v[182:183], v[182:183]
	v_pk_add_f32 v[184:185], v[150:151], v[0:1] op_sel_hi:[1,0] neg_lo:[0,1] neg_hi:[0,1]
	v_pk_add_f32 v[186:187], v[152:153], v[0:1] op_sel_hi:[1,0] neg_lo:[0,1] neg_hi:[0,1]
	v_pk_add_f32 v[146:147], v[160:161], v[0:1] op_sel_hi:[1,0] neg_lo:[0,1] neg_hi:[0,1]
	v_pk_add_f32 v[148:149], v[162:163], v[0:1] op_sel_hi:[1,0] neg_lo:[0,1] neg_hi:[0,1]
	v_pk_add_f32 v[150:151], v[164:165], v[0:1] op_sel_hi:[1,0] neg_lo:[0,1] neg_hi:[0,1]
	v_pk_add_f32 v[152:153], v[166:167], v[0:1] op_sel_hi:[1,0] neg_lo:[0,1] neg_hi:[0,1]
	v_pk_add_f32 v[80:81], v[168:169], v[0:1] op_sel_hi:[1,0] neg_lo:[0,1] neg_hi:[0,1]
	v_pk_add_f32 v[126:127], v[170:171], v[0:1] op_sel_hi:[1,0] neg_lo:[0,1] neg_hi:[0,1]
	v_pk_add_f32 v[128:129], v[174:175], v[0:1] op_sel_hi:[1,0] neg_lo:[0,1] neg_hi:[0,1]
	v_pk_add_f32 v[130:131], v[176:177], v[0:1] op_sel_hi:[1,0] neg_lo:[0,1] neg_hi:[0,1]
	v_pk_add_f32 v[68:69], v[70:71], v[0:1] op_sel_hi:[1,0] neg_lo:[0,1] neg_hi:[0,1]
	v_pk_add_f32 v[70:71], v[72:73], v[0:1] op_sel_hi:[1,0] neg_lo:[0,1] neg_hi:[0,1]
	v_pk_add_f32 v[74:75], v[114:115], v[0:1] op_sel_hi:[1,0] neg_lo:[0,1] neg_hi:[0,1]
	v_pk_add_f32 v[78:79], v[110:111], v[0:1] op_sel_hi:[1,0] neg_lo:[0,1] neg_hi:[0,1]
	v_add_f32_e32 v0, v216, v217
	v_add_f32_e32 v0, v218, v0
	v_pk_mul_f32 v[220:221], v[184:185], v[184:185]
	v_add_f32_e32 v0, v219, v0
	v_add_f32_e32 v0, v220, v0
	v_pk_mul_f32 v[222:223], v[186:187], v[186:187]
	v_add_f32_e32 v0, v221, v0
	v_add_f32_e32 v0, v222, v0
	v_pk_mul_f32 v[160:161], v[146:147], v[146:147]
	v_add_f32_e32 v0, v223, v0
	v_add_f32_e32 v0, v160, v0
	v_pk_mul_f32 v[162:163], v[148:149], v[148:149]
	v_add_f32_e32 v0, v161, v0
	v_add_f32_e32 v0, v162, v0
	v_pk_mul_f32 v[164:165], v[150:151], v[150:151]
	v_add_f32_e32 v0, v163, v0
	v_add_f32_e32 v0, v164, v0
	v_pk_mul_f32 v[166:167], v[152:153], v[152:153]
	v_add_f32_e32 v0, v165, v0
	v_add_f32_e32 v0, v166, v0
	v_pk_mul_f32 v[168:169], v[80:81], v[80:81]
	v_add_f32_e32 v0, v167, v0
	v_add_f32_e32 v0, v168, v0
	v_pk_mul_f32 v[170:171], v[126:127], v[126:127]
	v_add_f32_e32 v0, v169, v0
	v_add_f32_e32 v0, v170, v0
	v_pk_mul_f32 v[174:175], v[128:129], v[128:129]
	v_add_f32_e32 v0, v171, v0
	v_add_f32_e32 v0, v174, v0
	v_pk_mul_f32 v[176:177], v[130:131], v[130:131]
	v_add_f32_e32 v0, v175, v0
	v_add_f32_e32 v0, v176, v0
	v_pk_mul_f32 v[224:225], v[68:69], v[68:69]
	v_add_f32_e32 v0, v177, v0
	v_add_f32_e32 v0, v224, v0
	v_pk_mul_f32 v[226:227], v[70:71], v[70:71]
	v_add_f32_e32 v0, v225, v0
	v_add_f32_e32 v0, v226, v0
	v_pk_mul_f32 v[114:115], v[74:75], v[74:75]
	v_add_f32_e32 v0, v227, v0
	v_add_f32_e32 v0, v114, v0
	v_pk_mul_f32 v[110:111], v[78:79], v[78:79]
	v_add_f32_e32 v0, v115, v0
	v_add_f32_e32 v0, v110, v0
	v_add_f32_e32 v0, v111, v0
	ds_bpermute_b32 v110, v141, v0
	v_mul_f32_e32 v72, 0xbfb8aa3b, v179
	v_exp_f32_e32 v72, v72
	s_waitcnt lgkmcnt(0)
; __device__ __forceinline__ float bf2f(u16 h) { return __uint_as_float(((unsigned)h) << 16); }
; __device__ __forceinline__ float siluf(float x) { return x * __builtin_amdgcn_rcpf(1.f + __expf(-x)); }
; __device__ void hp_phase(const Ctx& p, const int hd) {
;     ...
;     q = wave_sum(q);
;     const float rs = rsqrtf(q * (1.f / 2048.f) + 1e-6f);
; #pragma unroll
;     for (int k = 0; k < 4; ++k) {
;       const int c = k * 512 + lane * 8;
;       uint4 ur = *(const uint4*)(Uh + row * LDQ + c);
;       uint4 zr = *(const uint4*)(cat + row * 8704 + hd * 2048 + c);
;       float u[8] = {bf2f(ur.x & 0xffff), bf2f(ur.x >> 16), bf2f(ur.y & 0xffff), bf2f(ur.y >> 16),
;                     bf2f(ur.z & 0xffff), bf2f(ur.z >> 16), bf2f(ur.w & 0xffff), bf2f(ur.w >> 16)};
;       float z[8] = {bf2f(zr.x & 0xffff), bf2f(zr.x >> 16), bf2f(zr.y & 0xffff), bf2f(zr.y >> 16),
;                     bf2f(zr.z & 0xffff), bf2f(zr.z >> 16), bf2f(zr.w & 0xffff), bf2f(zr.w >> 16)};
;       float o[8];
; #pragma unroll
;       for (int e = 0; e < 8; ++e) {
;         o[e] = (hv[k * 8 + e] * rs * ngr[k * 8 + e] + skr[k * 8 + e] * u[e]) * siluf(z[e]);
;       }
;       uint4 ov; ov.x = pack2(o[0], o[1]); ov.y = pack2(o[2], o[3]); ov.z = pack2(o[4], o[5]); ov.w = pack2(o[6], o[7]);
;       if (!p.dry) *(uint4*)(cat + row * 8704 + hd * 2048 + c) = ov;
;     }
	v_add_f32_e32 v0, v0, v110
	ds_bpermute_b32 v110, v211, v0
	v_add_f32_e32 v72, 1.0, v72
	v_rcp_f32_e32 v73, v72
	v_mul_f32_e32 v72, 0xbfb8aa3b, v178
	v_exp_f32_e32 v72, v72
	s_waitcnt lgkmcnt(0)
	v_add_f32_e32 v0, v0, v110
	ds_bpermute_b32 v110, v212, v0
	v_add_f32_e32 v72, 1.0, v72
	v_rcp_f32_e32 v72, v72
	s_waitcnt lgkmcnt(0)
	v_add_f32_e32 v0, v0, v110
	ds_bpermute_b32 v110, v213, v0
	v_pk_mul_f32 v[72:73], v[72:73], v[178:179]
	s_waitcnt lgkmcnt(0)
	v_add_f32_e32 v0, v0, v110
	ds_bpermute_b32 v110, v214, v0
	s_waitcnt lgkmcnt(0)
	v_add_f32_e32 v0, v0, v110
	ds_bpermute_b32 v110, v215, v0
	s_waitcnt lgkmcnt(0)
	v_add_f32_e32 v0, v0, v110
	v_mov_b32_e32 v110, 0x358637bd
	v_fmamk_f32 v0, v0, 0x3a000000, v110
	v_cmp_gt_f32_e32 vcc, s48, v0
	v_mul_f32_e32 v110, 0x4b800000, v0
	s_nop 0
	v_cndmask_b32_e32 v0, v0, v110, vcc
	v_rsq_f32_e32 v0, v0
	s_nop 0
	v_mul_f32_e32 v110, 0x45800000, v0
	v_cndmask_b32_e32 v0, v0, v110, vcc
	v_pk_mul_f32 v[110:111], v[186:187], v[0:1] op_sel_hi:[1,0]
	v_pk_mul_f32 v[80:81], v[80:81], v[0:1] op_sel_hi:[1,0]
	v_pk_mul_f32 v[110:111], v[8:9], v[110:111]
	v_pk_mul_f32 v[80:81], v[34:35], v[80:81]
	v_pk_fma_f32 v[102:103], v[16:17], v[102:103], v[110:111]
	v_pk_mul_f32 v[110:111], v[184:185], v[0:1] op_sel_hi:[1,0]
	v_pk_mul_f32 v[102:103], v[120:121], v[102:103]
	v_pk_mul_f32 v[110:111], v[6:7], v[110:111]
	v_pk_mul_f32 v[78:79], v[78:79], v[0:1] op_sel_hi:[1,0]
	v_pk_fma_f32 v[106:107], v[14:15], v[106:107], v[110:111]
	v_pk_mul_f32 v[110:111], v[182:183], v[0:1] op_sel_hi:[1,0]
	v_pk_mul_f32 v[106:107], v[116:117], v[106:107]
	v_pk_mul_f32 v[110:111], v[4:5], v[110:111]
	v_pk_mul_f32 v[78:79], v[60:61], v[78:79]
	v_pk_fma_f32 v[108:109], v[12:13], v[108:109], v[110:111]
	v_pk_mul_f32 v[110:111], v[180:181], v[0:1] op_sel_hi:[1,0]
	v_pk_mul_f32 v[108:109], v[112:113], v[108:109]
	v_pk_mul_f32 v[110:111], v[2:3], v[110:111]
	v_pk_mul_f32 v[74:75], v[74:75], v[0:1] op_sel_hi:[1,0]
	v_pk_fma_f32 v[104:105], v[10:11], v[104:105], v[110:111]
	v_pk_mul_f32 v[74:75], v[58:59], v[74:75]
	v_pk_mul_f32 v[110:111], v[118:119], v[104:105]
	v_cvt_pk_bf16_f32 v105, v102, v103
	v_cvt_pk_bf16_f32 v104, v106, v107
	v_cvt_pk_bf16_f32 v103, v108, v109
	v_cvt_pk_bf16_f32 v102, v110, v111
	global_store_dwordx4 v[98:99], v[102:105], off
	v_pk_mul_f32 v[108:109], v[152:153], v[0:1] op_sel_hi:[1,0]
	v_pk_mul_f32 v[110:111], v[148:149], v[0:1] op_sel_hi:[1,0]
	v_pk_mul_f32 v[108:109], v[24:25], v[108:109]
	v_pk_mul_f32 v[110:111], v[20:21], v[110:111]
	v_pk_mul_f32 v[70:71], v[70:71], v[0:1] op_sel_hi:[1,0]
	v_pk_mul_f32 v[68:69], v[68:69], v[0:1] op_sel_hi:[1,0]
	v_pk_mul_f32 v[70:71], v[52:53], v[70:71]
	s_waitcnt vmcnt(3) lgkmcnt(0)
	v_and_b32_e32 v107, 0xffff0000, v247
	v_lshlrev_b32_e32 v106, 16, v247
	v_pk_fma_f32 v[106:107], v[32:33], v[106:107], v[108:109]
	v_pk_mul_f32 v[108:109], v[150:151], v[0:1] op_sel_hi:[1,0]
	v_and_b32_e32 v105, 0xffff0000, v246
	v_pk_mul_f32 v[108:109], v[22:23], v[108:109]
	v_lshlrev_b32_e32 v104, 16, v246
	v_pk_fma_f32 v[104:105], v[30:31], v[104:105], v[108:109]
	v_pk_mul_f32 v[106:107], v[142:143], v[106:107]
	v_pk_mul_f32 v[108:109], v[132:133], v[104:105]
	v_and_b32_e32 v105, 0xffff0000, v245
	v_lshlrev_b32_e32 v104, 16, v245
	v_pk_fma_f32 v[104:105], v[28:29], v[104:105], v[110:111]
	v_and_b32_e32 v103, 0xffff0000, v244
	v_pk_mul_f32 v[110:111], v[122:123], v[104:105]
	v_pk_mul_f32 v[104:105], v[146:147], v[0:1] op_sel_hi:[1,0]
	v_lshlrev_b32_e32 v102, 16, v244
	v_pk_mul_f32 v[104:105], v[18:19], v[104:105]
	s_nop 0
	v_pk_fma_f32 v[102:103], v[26:27], v[102:103], v[104:105]
	v_cvt_pk_bf16_f32 v105, v106, v107
	v_pk_mul_f32 v[112:113], v[134:135], v[102:103]
	v_cvt_pk_bf16_f32 v104, v108, v109
	v_cvt_pk_bf16_f32 v103, v110, v111
	v_cvt_pk_bf16_f32 v102, v112, v113
	global_store_dwordx4 v[98:99], v[102:105], off offset:1024
	v_pk_mul_f32 v[108:109], v[130:131], v[0:1] op_sel_hi:[1,0]
	v_pk_mul_f32 v[110:111], v[126:127], v[0:1] op_sel_hi:[1,0]
	v_pk_mul_f32 v[108:109], v[44:45], v[108:109]
	v_pk_mul_f32 v[110:111], v[36:37], v[110:111]
	s_waitcnt vmcnt(3) lgkmcnt(0)
	v_and_b32_e32 v107, 0xffff0000, v251
	v_lshlrev_b32_e32 v106, 16, v251
	v_pk_fma_f32 v[106:107], v[48:49], v[106:107], v[108:109]
	v_pk_mul_f32 v[108:109], v[128:129], v[0:1] op_sel_hi:[1,0]
	v_and_b32_e32 v105, 0xffff0000, v250
	v_pk_mul_f32 v[108:109], v[42:43], v[108:109]
	v_lshlrev_b32_e32 v104, 16, v250
	v_pk_fma_f32 v[104:105], v[46:47], v[104:105], v[108:109]
	v_pk_mul_f32 v[106:107], v[158:159], v[106:107]
	v_pk_mul_f32 v[108:109], v[154:155], v[104:105]
	v_and_b32_e32 v105, 0xffff0000, v249
	v_lshlrev_b32_e32 v104, 16, v249
	v_and_b32_e32 v103, 0xffff0000, v248
	v_lshlrev_b32_e32 v102, 16, v248
	v_pk_fma_f32 v[104:105], v[40:41], v[104:105], v[110:111]
	v_pk_fma_f32 v[80:81], v[38:39], v[102:103], v[80:81]
	v_pk_mul_f32 v[110:111], v[144:145], v[104:105]
	v_pk_mul_f32 v[80:81], v[156:157], v[80:81]
	v_cvt_pk_bf16_f32 v105, v106, v107
	v_cvt_pk_bf16_f32 v104, v108, v109
	v_cvt_pk_bf16_f32 v103, v110, v111
	v_cvt_pk_bf16_f32 v102, v80, v81
	global_store_dwordx4 v[98:99], v[102:105], off offset:2048
	v_mul_f32_e32 v0, 0xbfb8aa3b, v124
	v_exp_f32_e32 v0, v0
	s_waitcnt vmcnt(3) lgkmcnt(0)
	v_and_b32_e32 v81, 0xffff0000, v231
	v_lshlrev_b32_e32 v80, 16, v231
	v_pk_fma_f32 v[78:79], v[64:65], v[80:81], v[78:79]
	v_add_f32_e32 v0, 1.0, v0
	v_pk_mul_f32 v[76:77], v[76:77], v[78:79]
	v_and_b32_e32 v79, 0xffff0000, v230
	v_lshlrev_b32_e32 v78, 16, v230
	v_pk_fma_f32 v[74:75], v[62:63], v[78:79], v[74:75]
	s_nop 0
	v_pk_mul_f32 v[72:73], v[74:75], v[72:73]
	v_and_b32_e32 v75, 0xffff0000, v229
	v_lshlrev_b32_e32 v74, 16, v229
	v_pk_fma_f32 v[70:71], v[56:57], v[74:75], v[70:71]
	v_rcp_f32_e32 v74, v0
	v_pk_mul_f32 v[66:67], v[70:71], v[66:67]
	v_mul_f32_e32 v70, 0xbfb8aa3b, v125
	v_exp_f32_e32 v70, v70
	v_and_b32_e32 v71, 0xffff0000, v228
	v_cvt_pk_bf16_f32 v67, v66, v67
	v_add_f32_e32 v70, 1.0, v70
	v_rcp_f32_e32 v75, v70
	v_lshlrev_b32_e32 v70, 16, v228
	v_pk_mul_f32 v[70:71], v[54:55], v[70:71]
	s_nop 0
	v_pk_fma_f32 v[68:69], v[50:51], v[68:69], v[70:71]
	v_pk_mul_f32 v[70:71], v[74:75], v[124:125]
	s_nop 0
	v_pk_mul_f32 v[70:71], v[68:69], v[70:71]
	v_cvt_pk_bf16_f32 v69, v76, v77
	v_cvt_pk_bf16_f32 v68, v72, v73
	v_cvt_pk_bf16_f32 v66, v70, v71
	global_store_dwordx4 v[98:99], v[66:69], off offset:3072
	s_cbranch_scc0 .LBB0_421
